# GEMM tails: counted wait for epilogue operands keeps the next tile's 24 prefetch loads in flight (was vmcnt(0))
# speedup vs baseline: 1.0245x; 1.0002x over previous
; #define LAS __attribute__((address_space(3)))
; #define LBAR() do { asm volatile("s_waitcnt lgkmcnt(0)" ::: "memory"); __builtin_amdgcn_s_barrier(); asm volatile("" ::: "memory"); } while (0)
; template <class Epi>
; __device__ __forceinline__ void gemm_tail(LAS unsigned char* lds_in, int wave_in, const Gemm g, const Epi& E) {
;     ...
;             for (int f = 0; f < 4; ++f) *(LAS f32x4*)(red + wid * 2048 + (16 * i + r) * 64 + 16 * f + 4 * q) = acc[i][f];
;         LBAR();
;         {
;             f32x4 v = (f32x4){0.f, 0.f, 0.f, 0.f};
; #pragma unroll
;             for (int w = 0; w < 8; ++w) v += *(const LAS f32x4*)(red + w * 2048 + rr * 64 + cc);
.LBB0_842:
	v_ashrrev_i32_e32 v137, 31, v136
	ds_write_b128 v144, v[98:101]
	ds_write_b128 v144, v[102:105] offset:64
	ds_write_b128 v144, v[106:109] offset:128
	ds_write_b128 v144, v[110:113] offset:192
	ds_write_b128 v144, v[114:117] offset:4096
	ds_write_b128 v144, v[118:121] offset:4160
	ds_write_b128 v144, v[122:125] offset:4224
	ds_write_b128 v144, v[126:129] offset:4288
	s_waitcnt lgkmcnt(0)
	s_barrier
	ds_read_b128 v[98:101], v141
	ds_read_b128 v[102:105], v141 offset:8192
	ds_read_b128 v[106:109], v141 offset:16384
	s_andn2_b64 vcc, exec, s[2:3]
	s_add_i32 s8, s8, s9
	s_waitcnt lgkmcnt(2)
	v_pk_add_f32 v[100:101], v[100:101], 0 op_sel_hi:[1,0]
	v_pk_add_f32 v[110:111], v[98:99], 0 op_sel_hi:[1,0]
	s_waitcnt lgkmcnt(1)
	v_pk_add_f32 v[104:105], v[100:101], v[104:105]
	ds_read_b128 v[98:101], v141 offset:24576
	v_pk_add_f32 v[110:111], v[110:111], v[102:103]
	s_waitcnt lgkmcnt(1)
	v_pk_add_f32 v[108:109], v[104:105], v[108:109]
	ds_read_b128 v[102:105], v141 offset:32768
	v_pk_add_f32 v[106:107], v[110:111], v[106:107]
	s_waitcnt lgkmcnt(1)
	v_pk_add_f32 v[108:109], v[108:109], v[100:101]
	v_pk_add_f32 v[110:111], v[106:107], v[98:99]
	ds_read_b128 v[98:101], v141 offset:40960
	s_waitcnt lgkmcnt(1)
	v_pk_add_f32 v[112:113], v[108:109], v[104:105]
	ds_read_b128 v[104:107], v141 offset:49152
	v_pk_add_f32 v[102:103], v[110:111], v[102:103]
	ds_read_b128 v[108:111], v141 offset:57344
	s_waitcnt lgkmcnt(2)
	v_pk_add_f32 v[98:99], v[102:103], v[98:99]
	s_cbranch_vccz .Ltail_g2a_drain
	s_waitcnt vmcnt(24)
	s_branch .Ltail_g2a_go

; #define LAS __attribute__((address_space(3)))
; __device__ __forceinline__ unsigned cvt_pk_bf16(float lo, float hi) { unsigned r; asm("v_cvt_pk_bf16_f32 %0, %1, %2" : "=v"(r) : "v"(lo), "v"(hi)); return r; }
; __device__ __forceinline__ float sigmoidf_(float x) { return __builtin_amdgcn_rcpf(1.0f + __expf(-x)); }
; #define LBAR() do { asm volatile("s_waitcnt lgkmcnt(0)" ::: "memory"); __builtin_amdgcn_s_barrier(); asm volatile("" ::: "memory"); } while (0)
;     __device__ __forceinline__ Pre tail4_pre(int row, int col) const { Pre p; p.gw = *(const u32x2*)(gate + (size_t)row * ldg + col); p.ow = (u32x2){0u, 0u};
;         if (MODE == 1) p.ow = *(const u32x2*)(O + (size_t)row * ldc + col); return p; }
;     __device__ __forceinline__ void tail4(const f32x4 v, const Pre& pre, int row, int col, int l16) const {
;         const u32x2 gw = pre.gw;
;         float v0 = sigmoidf_(bflo(gw.x)) * v[0], v1 = sigmoidf_(bfhi(gw.x)) * v[1], v2 = sigmoidf_(bflo(gw.y)) * v[2], v3 = sigmoidf_(bfhi(gw.y)) * v[3];
;         bf16_t* op = O + (size_t)row * ldc + col;
;         if (MODE == 1) { const u32x2 ow = pre.ow; v0 += bflo(ow.x); v1 += bfhi(ow.x); v2 += bflo(ow.y); v3 += bfhi(ow.y); }
;         u32x2 w; w.x = cvt_pk_bf16(v0, v1); w.y = cvt_pk_bf16(v2, v3);
;         *(u32x2*)op = w;
;     }
; template <class Epi>
; __device__ __forceinline__ void gemm_tail(LAS unsigned char* lds_in, int wave_in, const Gemm g, const Epi& E) {
;     ...
;             for (int w = 0; w < 8; ++w) v += *(const LAS f32x4*)(red + w * 2048 + rr * 64 + cc);
;             E.tail4(v, pre, row0 + rr, col0 + cc, lane);
;         }
;         LBAR();
.Ltail_g2a_go:
	v_lshlrev_b32_e32 v102, 16, v138
	v_and_b32_e32 v103, 0xffff0000, v138
	v_mul_f32_e32 v102, 0xbfb8aa3b, v102
	v_mul_f32_e32 v103, 0xbfb8aa3b, v103
	s_waitcnt lgkmcnt(1)
	v_pk_add_f32 v[98:99], v[98:99], v[104:105]
	v_exp_f32_e32 v102, v102
	v_exp_f32_e32 v103, v103
	v_and_b32_e32 v105, 0xffff0000, v139
	v_lshlrev_b32_e32 v104, 16, v139
	v_mul_f32_e32 v105, 0xbfb8aa3b, v105
	v_mul_f32_e32 v104, 0xbfb8aa3b, v104
	v_exp_f32_e32 v105, v105
	v_exp_f32_e32 v104, v104
	v_add_f32_e32 v102, 1.0, v102
	v_add_f32_e32 v103, 1.0, v103
	v_rcp_f32_e32 v102, v102
	v_rcp_f32_e32 v103, v103
	v_add_f32_e32 v105, 1.0, v105
	v_add_f32_e32 v104, 1.0, v104
	v_rcp_f32_e32 v105, v105
	v_pk_add_f32 v[100:101], v[112:113], v[100:101]
	s_waitcnt lgkmcnt(0)
	v_pk_add_f32 v[98:99], v[98:99], v[108:109]
	v_rcp_f32_e32 v104, v104
	v_pk_add_f32 v[100:101], v[100:101], v[106:107]
	v_mul_f32_e32 v102, v102, v98
	v_mul_f32_e32 v103, v103, v99
	v_lshlrev_b64 v[98:99], 11, v[136:137]
	v_pk_add_f32 v[100:101], v[100:101], v[110:111]
	v_lshl_add_u64 v[98:99], s[4:5], 0, v[98:99]
	v_mul_f32_e32 v101, v105, v101
	v_lshl_add_u64 v[98:99], v[134:135], 1, v[98:99]
	v_mul_f32_e32 v104, v104, v100
	v_cvt_pk_bf16_f32 v100, v102, v103
	v_cvt_pk_bf16_f32 v101, v104, v101
	global_store_dwordx2 v[98:99], v[100:101], off
	s_waitcnt lgkmcnt(0)
	s_barrier
	s_cbranch_vccz .LBB0_845

; #define LAS __attribute__((address_space(3)))
; #define LBAR() do { asm volatile("s_waitcnt lgkmcnt(0)" ::: "memory"); __builtin_amdgcn_s_barrier(); asm volatile("" ::: "memory"); } while (0)
; template <class Epi>
; __device__ __forceinline__ void gemm_tail(LAS unsigned char* lds_in, int wave_in, const Gemm g, const Epi& E) {
;     ...
;             for (int f = 0; f < 4; ++f) *(LAS f32x4*)(red + wid * 2048 + (16 * i + r) * 64 + 16 * f + 4 * q) = acc[i][f];
;         LBAR();
;         {
;             f32x4 v = (f32x4){0.f, 0.f, 0.f, 0.f};
; #pragma unroll
;             for (int w = 0; w < 8; ++w) v += *(const LAS f32x4*)(red + w * 2048 + rr * 64 + cc);
.LBB0_923:
	ds_write_b128 v145, v[98:101]
	ds_write_b128 v145, v[102:105] offset:64
	ds_write_b128 v145, v[106:109] offset:128
	ds_write_b128 v145, v[110:113] offset:192
	ds_write_b128 v145, v[114:117] offset:4096
	ds_write_b128 v145, v[118:121] offset:4160
	ds_write_b128 v145, v[122:125] offset:4224
	ds_write_b128 v145, v[126:129] offset:4288
	s_waitcnt lgkmcnt(0)
	s_barrier
	ds_read_b128 v[98:101], v141
	ds_read_b128 v[102:105], v141 offset:8192
	ds_read_b128 v[106:109], v141 offset:16384
	s_andn2_b64 vcc, exec, s[2:3]
	s_add_i32 s16, s16, s10
	s_waitcnt lgkmcnt(2)
	v_pk_add_f32 v[100:101], v[100:101], 0 op_sel_hi:[1,0]
	v_pk_add_f32 v[110:111], v[98:99], 0 op_sel_hi:[1,0]
	s_waitcnt lgkmcnt(1)
	v_pk_add_f32 v[104:105], v[100:101], v[104:105]
	ds_read_b128 v[98:101], v141 offset:24576
	v_pk_add_f32 v[110:111], v[110:111], v[102:103]
	s_waitcnt lgkmcnt(1)
	v_pk_add_f32 v[108:109], v[104:105], v[108:109]
	ds_read_b128 v[102:105], v141 offset:32768
	v_pk_add_f32 v[106:107], v[110:111], v[106:107]
	s_waitcnt lgkmcnt(1)
	v_pk_add_f32 v[108:109], v[108:109], v[100:101]
	v_pk_add_f32 v[110:111], v[106:107], v[98:99]
	ds_read_b128 v[98:101], v141 offset:40960
	s_waitcnt lgkmcnt(1)
	v_pk_add_f32 v[112:113], v[108:109], v[104:105]
	ds_read_b128 v[104:107], v141 offset:49152
	v_pk_add_f32 v[102:103], v[110:111], v[102:103]
	ds_read_b128 v[108:111], v141 offset:57344
	s_waitcnt lgkmcnt(2)
	v_pk_add_f32 v[98:99], v[102:103], v[98:99]
	s_cbranch_vccz .Ltail_g2b_drain1
	s_waitcnt vmcnt(25)
	s_branch .Ltail_g2b_go1

; __device__ __forceinline__ unsigned cvt_pk_bf16(float lo, float hi) { unsigned r; asm("v_cvt_pk_bf16_f32 %0, %1, %2" : "=v"(r) : "v"(lo), "v"(hi)); return r; }
; __device__ __forceinline__ float sigmoidf_(float x) { return __builtin_amdgcn_rcpf(1.0f + __expf(-x)); }
;     __device__ __forceinline__ void tail4(const f32x4 v, const Pre& pre, int row, int col, int l16) const {
;         const u32x2 gw = pre.gw;
;         float v0 = sigmoidf_(bflo(gw.x)) * v[0], v1 = sigmoidf_(bfhi(gw.x)) * v[1], v2 = sigmoidf_(bflo(gw.y)) * v[2], v3 = sigmoidf_(bfhi(gw.y)) * v[3];
;         bf16_t* op = O + (size_t)row * ldc + col;
;         if (MODE == 1) { const u32x2 ow = pre.ow; v0 += bflo(ow.x); v1 += bfhi(ow.x); v2 += bflo(ow.y); v3 += bfhi(ow.y); }
;         u32x2 w; w.x = cvt_pk_bf16(v0, v1); w.y = cvt_pk_bf16(v2, v3);
.Ltail_g2b_go1:
	v_lshlrev_b32_e32 v102, 16, v138
	v_mul_f32_e32 v102, 0xbfb8aa3b, v102
	v_and_b32_e32 v103, 0xffff0000, v138
	s_waitcnt lgkmcnt(1)
	v_pk_add_f32 v[98:99], v[98:99], v[104:105]
	v_exp_f32_e32 v102, v102
	v_mul_f32_e32 v103, 0xbfb8aa3b, v103
	v_lshlrev_b32_e32 v104, 16, v139
	v_exp_f32_e32 v103, v103
	v_mul_f32_e32 v104, 0xbfb8aa3b, v104
	v_and_b32_e32 v105, 0xffff0000, v139
	v_exp_f32_e32 v104, v104
	v_mul_f32_e32 v105, 0xbfb8aa3b, v105
	v_exp_f32_e32 v105, v105
	v_add_f32_e32 v102, 1.0, v102
	v_rcp_f32_e32 v102, v102
	v_add_f32_e32 v103, 1.0, v103
	v_rcp_f32_e32 v103, v103
	v_add_f32_e32 v104, 1.0, v104
	v_pk_add_f32 v[100:101], v[112:113], v[100:101]
	v_rcp_f32_e32 v104, v104
	v_add_f32_e32 v105, 1.0, v105
	v_pk_add_f32 v[100:101], v[100:101], v[106:107]
	s_waitcnt lgkmcnt(0)
	v_pk_add_f32 v[98:99], v[98:99], v[108:109]
	v_rcp_f32_e32 v105, v105
	s_cbranch_vccz .Ltail_g2b_drain0
	s_waitcnt vmcnt(24)
	s_branch .Ltail_g2b_go0

; #define LAS __attribute__((address_space(3)))
; __device__ __forceinline__ unsigned cvt_pk_bf16(float lo, float hi) { unsigned r; asm("v_cvt_pk_bf16_f32 %0, %1, %2" : "=v"(r) : "v"(lo), "v"(hi)); return r; }
; __device__ __forceinline__ float sigmoidf_(float x) { return __builtin_amdgcn_rcpf(1.0f + __expf(-x)); }
; #define LBAR() do { asm volatile("s_waitcnt lgkmcnt(0)" ::: "memory"); __builtin_amdgcn_s_barrier(); asm volatile("" ::: "memory"); } while (0)
;     __device__ __forceinline__ void tail4(const f32x4 v, const Pre& pre, int row, int col, int l16) const {
;         const u32x2 gw = pre.gw;
;         float v0 = sigmoidf_(bflo(gw.x)) * v[0], v1 = sigmoidf_(bfhi(gw.x)) * v[1], v2 = sigmoidf_(bflo(gw.y)) * v[2], v3 = sigmoidf_(bfhi(gw.y)) * v[3];
;         bf16_t* op = O + (size_t)row * ldc + col;
;         if (MODE == 1) { const u32x2 ow = pre.ow; v0 += bflo(ow.x); v1 += bfhi(ow.x); v2 += bflo(ow.y); v3 += bfhi(ow.y); }
;         u32x2 w; w.x = cvt_pk_bf16(v0, v1); w.y = cvt_pk_bf16(v2, v3);
;         *(u32x2*)op = w;
; template <class Epi>
; __device__ __forceinline__ void gemm_tail(LAS unsigned char* lds_in, int wave_in, const Gemm g, const Epi& E) {
;     ...
;             for (int w = 0; w < 8; ++w) v += *(const LAS f32x4*)(red + w * 2048 + rr * 64 + cc);
;             E.tail4(v, pre, row0 + rr, col0 + cc, lane);
;         }
;         LBAR();
.Ltail_g2b_go0:
	v_lshlrev_b32_e32 v106, 16, v136
	v_fmac_f32_e32 v106, v102, v98
	v_and_b32_e32 v98, 0xffff0000, v136
	v_pk_add_f32 v[100:101], v[100:101], v[110:111]
	v_fmac_f32_e32 v98, v103, v99
	v_lshlrev_b32_e32 v99, 16, v137
	v_fmac_f32_e32 v99, v104, v100
	v_and_b32_e32 v100, 0xffff0000, v137
	v_fmac_f32_e32 v100, v105, v101
	v_cvt_pk_bf16_f32 v98, v106, v98
	v_cvt_pk_bf16_f32 v99, v99, v100
	global_store_dwordx2 v[134:135], v[98:99], off
	s_waitcnt lgkmcnt(0)
	s_barrier
	s_cbranch_vccz .LBB0_926

; #define LAS __attribute__((address_space(3)))
; #define LBAR() do { asm volatile("s_waitcnt lgkmcnt(0)" ::: "memory"); __builtin_amdgcn_s_barrier(); asm volatile("" ::: "memory"); } while (0)
; template <class Epi>
; __device__ __forceinline__ void gemm_tail(LAS unsigned char* lds_in, int wave_in, const Gemm g, const Epi& E) {
;     ...
;             for (int f = 0; f < 4; ++f) *(LAS f32x4*)(red + wid * 2048 + (16 * i + r) * 64 + 16 * f + 4 * q) = acc[i][f];
;         LBAR();
;         {
;             f32x4 v = (f32x4){0.f, 0.f, 0.f, 0.f};
; #pragma unroll
;             for (int w = 0; w < 8; ++w) v += *(const LAS f32x4*)(red + w * 2048 + rr * 64 + cc);
.LBB0_1026:
	ds_write_b128 v152, v[102:105]
	ds_write_b128 v152, v[106:109] offset:64
	ds_write_b128 v152, v[110:113] offset:128
	ds_write_b128 v152, v[114:117] offset:192
	ds_write_b128 v152, v[118:121] offset:4096
	ds_write_b128 v152, v[122:125] offset:4160
	ds_write_b128 v152, v[126:129] offset:4224
	ds_write_b128 v152, v[130:133] offset:4288
	s_waitcnt lgkmcnt(0)
	s_barrier
	ds_read_b128 v[102:105], v145
	ds_read_b128 v[106:109], v145 offset:8192
	ds_read_b128 v[110:113], v145 offset:16384
	s_waitcnt lgkmcnt(2)
	v_pk_add_f32 v[104:105], v[104:105], 0 op_sel_hi:[1,0]
	v_pk_add_f32 v[114:115], v[102:103], 0 op_sel_hi:[1,0]
	s_waitcnt lgkmcnt(1)
	v_pk_add_f32 v[108:109], v[104:105], v[108:109]
	ds_read_b128 v[102:105], v145 offset:24576
	v_pk_add_f32 v[114:115], v[114:115], v[106:107]
	s_waitcnt lgkmcnt(1)
	v_pk_add_f32 v[112:113], v[108:109], v[112:113]
	ds_read_b128 v[106:109], v145 offset:32768
	v_pk_add_f32 v[110:111], v[114:115], v[110:111]
	s_waitcnt lgkmcnt(1)
	v_pk_add_f32 v[112:113], v[112:113], v[104:105]
	v_pk_add_f32 v[114:115], v[110:111], v[102:103]
	ds_read_b128 v[102:105], v145 offset:40960
	s_waitcnt lgkmcnt(1)
	v_pk_add_f32 v[116:117], v[112:113], v[108:109]
	ds_read_b128 v[108:111], v145 offset:49152
	v_pk_add_f32 v[106:107], v[114:115], v[106:107]
	ds_read_b128 v[112:115], v145 offset:57344
	s_waitcnt lgkmcnt(2)
	v_pk_add_f32 v[104:105], v[116:117], v[104:105]
	v_pk_add_f32 v[102:103], v[106:107], v[102:103]
	s_waitcnt lgkmcnt(1)
	v_pk_add_f32 v[104:105], v[104:105], v[110:111]
	v_pk_add_f32 v[102:103], v[102:103], v[108:109]
	s_waitcnt lgkmcnt(0)
	v_pk_add_f32 v[104:105], v[104:105], v[114:115]
	v_pk_add_f32 v[102:103], v[102:103], v[112:113]
	s_and_b64 vcc, exec, s[12:13]
	s_cbranch_vccnz .Ltail_g3_drain
	s_waitcnt vmcnt(24)
	s_branch .Ltail_g3_go

; __device__ __forceinline__ unsigned cvt_pk_bf16(float lo, float hi) { unsigned r; asm("v_cvt_pk_bf16_f32 %0, %1, %2" : "=v"(r) : "v"(lo), "v"(hi)); return r; }
; __device__ __forceinline__ float shx(float v, int m, int lane) { return __builtin_bit_cast(float, __builtin_amdgcn_ds_bpermute((lane ^ m) << 2, __builtin_bit_cast(int, v))); }
;     __device__ __forceinline__ void tail4(const f32x4 v, const Pre& pre, int row, int col, int l16) const {
;         float* xp = X + (size_t)row * DM + col;
;         f32x4 x0 = pre.x; x0 += v; *(f32x4*)xp = x0;
;         float ss = (x0[0] * x0[0] + x0[1] * x0[1]) + (x0[2] * x0[2] + x0[3] * x0[3]);
;         u32x2 w; w.x = cvt_pk_bf16(x0[0], x0[1]); w.y = cvt_pk_bf16(x0[2], x0[3]);
;         *(u32x2*)(XB + (size_t)row * DM + col) = w;
;         ss += shx(ss, 1, l16); ss += shx(ss, 2, l16); ss += shx(ss, 4, l16); ss += shx(ss, 8, l16);
;         if ((l16 & 15) == 0) rss[(size_t)row * 16 + (col >> 6)] = ss;
;     }
.Ltail_g3_go:
	v_pk_add_f32 v[100:101], v[100:101], v[104:105]
	v_pk_add_f32 v[98:99], v[98:99], v[102:103]
	v_mul_f32_e32 v103, v101, v101
	v_mul_f32_e32 v102, v99, v99
	v_fmac_f32_e32 v102, v98, v98
	v_fmac_f32_e32 v103, v100, v100
	v_add_f32_e32 v102, v102, v103
	ds_bpermute_b32 v103, v146, v102
	global_store_dwordx4 v[142:143], v[98:101], off
	s_waitcnt lgkmcnt(0)
	v_add_f32_e32 v102, v102, v103
	ds_bpermute_b32 v103, v147, v102
	s_waitcnt lgkmcnt(0)
	v_add_f32_e32 v104, v102, v103
	ds_bpermute_b32 v105, v148, v104
	v_cvt_pk_bf16_f32 v102, v98, v99
	v_cvt_pk_bf16_f32 v103, v100, v101
	v_lshlrev_b64 v[100:101], 11, v[138:139]
	v_lshl_add_u64 v[100:101], s[8:9], 0, v[100:101]
	s_waitcnt lgkmcnt(0)
	v_add_f32_e32 v98, v104, v105
	ds_bpermute_b32 v99, v149, v98
	v_lshl_add_u64 v[100:101], v[140:141], 1, v[100:101]
	global_store_dwordx2 v[100:101], v[102:103], off
	s_and_saveexec_b64 s[14:15], s[2:3]
	s_cbranch_execz .LBB0_1023
	v_lshlrev_b64 v[100:101], 6, v[138:139]
	v_lshl_add_u64 v[100:101], s[10:11], 0, v[100:101]
	s_ashr_i32 s5, s4, 31
	v_lshl_add_u64 v[100:101], s[4:5], 2, v[100:101]
	s_waitcnt lgkmcnt(0)
	v_add_f32_e32 v98, v98, v99
	global_store_dword v[100:101], v98, off
	s_branch .LBB0_1023

; #define LAS __attribute__((address_space(3)))
; #define LBAR() do { asm volatile("s_waitcnt lgkmcnt(0)" ::: "memory"); __builtin_amdgcn_s_barrier(); asm volatile("" ::: "memory"); } while (0)
; template <class Epi>
; __device__ __forceinline__ void gemm_tail(LAS unsigned char* lds_in, int wave_in, const Gemm g, const Epi& E) {
;     ...
;             for (int f = 0; f < 4; ++f) *(LAS f32x4*)(red + wid * 2048 + (16 * i + r) * 64 + 16 * f + 4 * q) = acc[i][f];
;         LBAR();
;         {
;             f32x4 v = (f32x4){0.f, 0.f, 0.f, 0.f};
; #pragma unroll
;             for (int w = 0; w < 8; ++w) v += *(const LAS f32x4*)(red + w * 2048 + rr * 64 + cc);
.LBB0_1289:
	ds_write_b128 v165, v[110:113]
	ds_write_b128 v165, v[114:117] offset:64
	ds_write_b128 v165, v[118:121] offset:128
	ds_write_b128 v165, v[106:109] offset:192
	ds_write_b128 v165, v[122:125] offset:4096
	ds_write_b128 v165, v[102:105] offset:4160
	ds_write_b128 v165, v[126:129] offset:4224
	ds_write_b128 v165, v[130:133] offset:4288
	s_waitcnt lgkmcnt(0)
	s_barrier
	ds_read_b128 v[102:105], v157
	ds_read_b128 v[106:109], v157 offset:8192
	ds_read_b128 v[110:113], v157 offset:16384
	s_waitcnt lgkmcnt(2)
	v_pk_add_f32 v[104:105], v[104:105], 0 op_sel_hi:[1,0]
	v_pk_add_f32 v[114:115], v[102:103], 0 op_sel_hi:[1,0]
	s_waitcnt lgkmcnt(1)
	v_pk_add_f32 v[108:109], v[104:105], v[108:109]
	ds_read_b128 v[102:105], v157 offset:24576
	v_pk_add_f32 v[114:115], v[114:115], v[106:107]
	s_waitcnt lgkmcnt(1)
	v_pk_add_f32 v[112:113], v[108:109], v[112:113]
	ds_read_b128 v[106:109], v157 offset:32768
	v_pk_add_f32 v[110:111], v[114:115], v[110:111]
	s_waitcnt lgkmcnt(1)
	v_pk_add_f32 v[112:113], v[112:113], v[104:105]
	v_pk_add_f32 v[114:115], v[110:111], v[102:103]
	ds_read_b128 v[102:105], v157 offset:40960
	s_waitcnt lgkmcnt(1)
	v_pk_add_f32 v[116:117], v[112:113], v[108:109]
	ds_read_b128 v[108:111], v157 offset:49152
	v_pk_add_f32 v[106:107], v[114:115], v[106:107]
	ds_read_b128 v[112:115], v157 offset:57344
	s_waitcnt lgkmcnt(2)
	v_pk_add_f32 v[104:105], v[116:117], v[104:105]
	v_pk_add_f32 v[102:103], v[106:107], v[102:103]
	s_waitcnt lgkmcnt(1)
	v_pk_add_f32 v[104:105], v[104:105], v[110:111]
	v_pk_add_f32 v[102:103], v[102:103], v[108:109]
	s_waitcnt lgkmcnt(0)
	v_pk_add_f32 v[104:105], v[104:105], v[114:115]
	v_pk_add_f32 v[102:103], v[102:103], v[112:113]
	s_and_b64 vcc, exec, s[6:7]
	s_cbranch_vccnz .Ltail_g5_drain
	s_waitcnt vmcnt(24)
	s_branch .Ltail_g5_go

; __device__ __forceinline__ unsigned cvt_pk_bf16(float lo, float hi) { unsigned r; asm("v_cvt_pk_bf16_f32 %0, %1, %2" : "=v"(r) : "v"(lo), "v"(hi)); return r; }
; __device__ __forceinline__ float shx(float v, int m, int lane) { return __builtin_bit_cast(float, __builtin_amdgcn_ds_bpermute((lane ^ m) << 2, __builtin_bit_cast(int, v))); }
;     __device__ __forceinline__ void tail4(const f32x4 v, const Pre& pre, int row, int col, int l16) const {
;         float* xp = X + (size_t)row * DM + col;
;         f32x4 x0 = pre.x; x0 += v; *(f32x4*)xp = x0;
;         float ss = (x0[0] * x0[0] + x0[1] * x0[1]) + (x0[2] * x0[2] + x0[3] * x0[3]);
;         u32x2 w; w.x = cvt_pk_bf16(x0[0], x0[1]); w.y = cvt_pk_bf16(x0[2], x0[3]);
;         *(u32x2*)(XB + (size_t)row * DM + col) = w;
;         ss += shx(ss, 1, l16); ss += shx(ss, 2, l16); ss += shx(ss, 4, l16); ss += shx(ss, 8, l16);
;         if ((l16 & 15) == 0) rss[(size_t)row * 16 + (col >> 6)] = ss;
;     }
.Ltail_g5_go:
	v_pk_add_f32 v[100:101], v[100:101], v[104:105]
	v_pk_add_f32 v[98:99], v[98:99], v[102:103]
	v_mul_f32_e32 v103, v101, v101
	v_mul_f32_e32 v102, v99, v99
	v_fmac_f32_e32 v102, v98, v98
	v_fmac_f32_e32 v103, v100, v100
	v_add_f32_e32 v102, v102, v103
	ds_bpermute_b32 v103, v158, v102
	global_store_dwordx4 v[138:139], v[98:101], off
	s_waitcnt lgkmcnt(0)
	v_add_f32_e32 v102, v102, v103
	ds_bpermute_b32 v103, v159, v102
	s_waitcnt lgkmcnt(0)
	v_add_f32_e32 v104, v102, v103
	ds_bpermute_b32 v105, v160, v104
	v_cvt_pk_bf16_f32 v102, v98, v99
	v_cvt_pk_bf16_f32 v103, v100, v101
	v_lshlrev_b64 v[100:101], 11, v[134:135]
	v_lshl_add_u64 v[100:101], s[10:11], 0, v[100:101]
	s_waitcnt lgkmcnt(0)
	v_add_f32_e32 v98, v104, v105
	ds_bpermute_b32 v99, v161, v98
	v_lshl_add_u64 v[100:101], v[136:137], 1, v[100:101]
	global_store_dwordx2 v[100:101], v[102:103], off
	s_and_saveexec_b64 s[14:15], s[2:3]
	s_cbranch_execz .LBB0_1286
	v_lshlrev_b64 v[100:101], 6, v[134:135]
	v_lshl_add_u64 v[100:101], s[12:13], 0, v[100:101]
	s_ashr_i32 s5, s4, 31
	v_lshl_add_u64 v[100:101], s[4:5], 2, v[100:101]
	s_waitcnt lgkmcnt(0)
	v_add_f32_e32 v98, v98, v99
	global_store_dword v[100:101], v98, off
	s_branch .LBB0_1286
